# compression-MLP tasks split over 4 waves each along the contraction (LDS reduction), all 8 waves busy
# baseline (speedup 1.0000x reference)
; __device__ __forceinline__ void compress_task(CArgs* Ap, int l, int task, int lane) {
;     unsigned char* ws = Ap->ws;
;     const int kv = task & 1, nb = (task >> 1) & 31, g = (task >> 6) & 3, b = task >> 8;
;     const int n16 = lane & 15, g4 = lane >> 4;
;     const bf16_t* P = (const bf16_t*)(ws + p_off(l));
;     const bf16_t* W1t = (const bf16_t*)(ws + WS_CW1) + (size_t)(l * 2 + kv) * 128 * 2048;
;     const bf16_t* W2t = (const bf16_t*)(ws + WS_CW2) + (size_t)(l * 2 + kv) * 64 * 128;
;     const float* pos = Ap->in[kv ? 19 : 16] + (size_t)l * 32 * 64;
;     const int n = nb * 16 + n16;
;     const int colb = (kv ? C_VC : C_KC) + g * 64;
;     f32x4 acc[8];
; __global__ void __launch_bounds__(512, 2) hymba_fwd(Args A_unused) {
;     ...
;             for (int wt = blk; wt < 256; wt += G) { const int b_ = wt >> 7, cp_ = (wt >> 4) & 7, gq_ = wt & 15;
;                 s5_task<1>(Ap, l, b_, 4 * gq_ + (wave & 3), 2 * cp_ + (wave >> 2), lds + wave * 8192, lane); }
;             if (wave < 2) for (int task = blk * 2 + wave; task < 512; task += G * 2) compress_task(Ap, l, task, lane);
.LBB0_830:
	s_and_b32 s47, s16, 3
	s_lshr_b32 s16, s16, 2
	s_lshl_b32 s19, s16, 6
	s_cmp_lt_i32 s16, 2
	s_cbranch_scc0 .LBB0_852
	s_lshl_b32 s2, s18, 1
	s_add_i32 s10, s2, s16
	s_cmpk_gt_i32 s10, 0x1ff
	s_cbranch_scc1 .LBB0_852
	s_load_dwordx2 s[2:3], s[0:1], 0xd8
	v_readlane_b32 s4, v254, 4
	v_readlane_b32 s5, v254, 5
	s_lshl_b32 s6, s4, 1
	s_lshl_b64 s[4:5], s[4:5], 20
	s_waitcnt lgkmcnt(0)
	s_add_u32 s4, s2, s4
	s_addc_u32 s5, s3, s5
	s_add_u32 s11, s4, 0x2a200000
	s_addc_u32 s12, s5, 0
	s_add_u32 s13, s4, 0x2a600000
	s_addc_u32 s14, s5, 0
	s_bfe_u32 s8, s19, 0x10006
	s_lshl_b32 s15, s17, 1
	s_or_b32 s72, s8, s6
	s_bitcmp1_b32 s19, 6
	v_lshrrev_b32_e32 v0, 4, v4
	s_cselect_b64 s[4:5], -1, 0
	s_cmp_eq_u32 s8, 0
	s_movk_i32 s6, 0x98
	v_and_b32_e32 v2, 15, v5
	v_lshlrev_b32_e32 v144, 3, v0
	s_cselect_b32 s6, 0x80, s6
	s_movk_i32 s7, 0x900
	v_lshlrev_b32_e32 v6, 2, v0
	v_lshl_add_u64 v[0:1], s[2:3], 0, v[144:145]
	v_lshlrev_b32_e32 v144, 8, v2
	s_cselect_b32 s9, 0x800, s7
	s_add_u32 s0, s0, s6
	v_lshl_add_u64 v[0:1], v[0:1], 0, v[144:145]
	s_addc_u32 s1, s1, 0
	s_lshl_b64 s[6:7], s[72:73], 14
	v_lshl_add_u64 v[0:1], v[0:1], 0, s[6:7]
	s_mov_b64 s[6:7], 0x17900000
	v_lshl_add_u64 v[60:61], v[0:1], 0, s[6:7]
	s_mov_b64 s[6:7], 0x17901000
	v_lshl_add_u64 v[62:63], v[0:1], 0, s[6:7]
	s_mov_b64 s[6:7], 0x17901020
	v_lshl_add_u64 v[64:65], v[0:1], 0, s[6:7]
	s_mov_b64 s[6:7], 0x17901040
	v_lshl_add_u64 v[66:67], v[0:1], 0, s[6:7]
	s_mov_b64 s[6:7], 0x17901060
	v_lshl_add_u64 v[68:69], v[0:1], 0, s[6:7]
	s_mov_b64 s[6:7], 0x17901080
	v_lshl_add_u64 v[70:71], v[0:1], 0, s[6:7]
	s_mov_b64 s[6:7], 0x179010a0
	v_lshl_add_u64 v[72:73], v[0:1], 0, s[6:7]
	s_mov_b64 s[6:7], 0x179010c0
	v_lshl_add_u64 v[74:75], v[0:1], 0, s[6:7]
	s_mov_b64 s[6:7], 0x179010e0
	v_lshl_add_u64 v[76:77], v[0:1], 0, s[6:7]
	s_mov_b64 s[6:7], 0x17902000
	v_lshl_add_u64 v[78:79], v[0:1], 0, s[6:7]
	s_mov_b64 s[6:7], 0x17902020
	v_lshl_add_u64 v[80:81], v[0:1], 0, s[6:7]
	s_mov_b64 s[6:7], 0x17902040
	v_lshl_add_u64 v[82:83], v[0:1], 0, s[6:7]
	s_mov_b64 s[6:7], 0x17902060
	v_lshl_add_u64 v[84:85], v[0:1], 0, s[6:7]
	s_mov_b64 s[6:7], 0x17902080
	v_lshl_add_u64 v[86:87], v[0:1], 0, s[6:7]
	s_mov_b64 s[6:7], 0x179020a0
	v_lshl_add_u64 v[88:89], v[0:1], 0, s[6:7]
	s_mov_b64 s[6:7], 0x179020c0
	v_lshl_add_u64 v[90:91], v[0:1], 0, s[6:7]
	s_mov_b64 s[6:7], 0x179020e0
	v_lshl_add_u64 v[92:93], v[0:1], 0, s[6:7]
	s_mov_b64 s[6:7], 0x17903000
	v_lshl_add_u64 v[94:95], v[0:1], 0, s[6:7]
	s_mov_b64 s[6:7], 0x17903020
	v_lshl_add_u64 v[96:97], v[0:1], 0, s[6:7]
	s_mov_b64 s[6:7], 0x17903040
	v_lshl_add_u64 v[98:99], v[0:1], 0, s[6:7]
	s_mov_b64 s[6:7], 0x17903060
	v_lshl_add_u64 v[100:101], v[0:1], 0, s[6:7]
	s_mov_b64 s[6:7], 0x17903080
	v_lshl_add_u64 v[102:103], v[0:1], 0, s[6:7]
	s_mov_b64 s[6:7], 0x179030a0
	v_lshl_add_u64 v[104:105], v[0:1], 0, s[6:7]
	s_mov_b64 s[6:7], 0x179030c0
	v_lshl_add_u64 v[106:107], v[0:1], 0, s[6:7]
	s_mov_b64 s[6:7], 0x179030e0
	v_lshl_add_u64 v[108:109], v[0:1], 0, s[6:7]
	v_and_b32_e32 v144, 48, v4
	v_readlane_b32 s6, v254, 0
	v_lshrrev_b32_e32 v3, 1, v4
	v_lshlrev_b32_e32 v7, 2, v4
	s_load_dwordx2 s[0:1], s[0:1], 0x0
	v_lshl_add_u64 v[0:1], s[2:3], 0, v[144:145]
	s_add_i32 s72, s6, s8
	v_bfe_u32 v4, v5, 4, 2
	v_lshl_add_u64 v[110:111], v[0:1], 0, s[96:97]
	s_lshl_b64 s[6:7], s[72:73], 19
	v_lshlrev_b32_e32 v0, 12, v2
	v_lshlrev_b32_e32 v1, 4, v4
	v_or3_b32 v0, s6, v0, v1
	v_mov_b32_e32 v1, s7
	v_lshl_add_u64 v[112:113], s[2:3], 0, v[0:1]
	s_lshl_b32 s2, s18, 4
	s_lshl_b32 s3, s16, 3
	s_add_i32 s16, s2, s3
	s_lshl_b32 s17, s17, 4
	v_readlane_b32 s2, v254, 2
	v_and_b32_e32 v131, 4, v6
	v_and_or_b32 v132, v3, 16, v2
	v_readlane_b32 s3, v254, 3
	s_waitcnt lgkmcnt(0)
	s_add_u32 s0, s0, s2
	v_lshl_or_b32 v3, v132, 3, v131
	v_lshlrev_b32_e32 v144, 5, v4
	s_addc_u32 s1, s1, s3
	v_and_b32_e32 v130, 3, v5
	v_and_or_b32 v133, v7, 48, v6
	v_lshlrev_b32_e32 v134, 4, v2
	v_lshl_add_u64 v[114:115], s[0:1], 0, v[144:145]
	s_lshl_b32 s18, s9, 1
	v_lshlrev_b32_e32 v135, 1, v3
	s_branch .LBB0_834

; __device__ __forceinline__ unsigned pk2(float lo, float hi) { return pg8::cvt_pk_bf16(lo, hi); }
; __device__ __forceinline__ float bflo(unsigned w) { return __uint_as_float(w << 16); }
; __device__ __forceinline__ float bfhi(unsigned w) { return __uint_as_float(w & 0xffff0000u); }
; __device__ __forceinline__ void compress_task(CArgs* Ap, int l, int task, int lane) {
;     ...
; #pragma unroll 2
;     for (int ks = 0; ks < 64; ++ks) {
;         const int itok = ks >> 1, d0 = 32 * (ks & 1) + 8 * g4;
;         int tok = 16 * n + itok; tok = tok > SEQ - 1 ? SEQ - 1 : tok;
;         const u32x4 raw = *(const u32x4*)(P + ((size_t)b * SEQ + tok) * NINP + colb + d0);
;         const f32x4 p0 = *(const f32x4*)(pos + itok * 64 + d0), p1 = *(const f32x4*)(pos + itok * 64 + d0 + 4);
;         u32x4 w;
;         w.x = pk2(bflo(raw.x) + p0[0], bfhi(raw.x) + p0[1]); w.y = pk2(bflo(raw.y) + p0[2], bfhi(raw.y) + p0[3]);
;         w.z = pk2(bflo(raw.z) + p1[0], bfhi(raw.z) + p1[1]); w.w = pk2(bflo(raw.w) + p1[2], bfhi(raw.w) + p1[3]);
;         const bf16x8 fb = __builtin_bit_cast(bf16x8, w);
; #pragma unroll
;         for (int h = 0; h < 8; ++h) { const bf16x8 wa = *(const bf16x8*)(W1t + (size_t)(16 * h + n16) * 2048 + 32 * ks + 8 * g4); acc[h] = __builtin_amdgcn_mfma_f32_16x16x32_bf16(wa, fb, acc[h], 0, 0, 0); }
;     }
.LBB0_834:
	s_lshl_b32 s0, s16, 4
	s_and_b32 s0, s0, 0x1f00
	v_or_b32_e32 v136, s0, v134
	s_lshl_b32 s49, s47, 3
	v_add_u32_e32 v136, s49, v136
	s_ashr_i32 s0, s10, 8
	s_bfe_u32 s8, s10, 0x20006
	s_ashr_i32 s1, s0, 31
	s_lshl_b64 s[2:3], s[0:1], 13
	s_lshl_b32 s1, s8, 7
	s_or_b32 s72, s1, s18
	v_mov_b32_e32 v20, 0
	v_lshl_add_u64 v[116:117], v[110:111], 0, s[72:73]
	s_lshl_b32 s6, s47, 10
	s_mov_b32 s7, 0
	s_add_i32 s48, s6, 0x400
	s_lshl_b32 s50, s47, 11
	s_mov_b32 s51, 0
	v_lshl_add_u64 v[118:119], v[114:115], 0, s[50:51]
	v_mov_b32_e32 v21, v20
	v_mov_b32_e32 v22, v20
	v_mov_b32_e32 v23, v20
	v_mov_b32_e32 v24, v20
	v_mov_b32_e32 v25, v20
	v_mov_b32_e32 v26, v20
	v_mov_b32_e32 v27, v20
	v_mov_b32_e32 v16, v20
	v_mov_b32_e32 v17, v20
	v_mov_b32_e32 v18, v20
	v_mov_b32_e32 v19, v20
	v_mov_b32_e32 v28, v20
	v_mov_b32_e32 v29, v20
	v_mov_b32_e32 v30, v20
	v_mov_b32_e32 v31, v20
	v_mov_b32_e32 v12, v20
	v_mov_b32_e32 v13, v20
	v_mov_b32_e32 v14, v20
	v_mov_b32_e32 v15, v20
	v_mov_b32_e32 v8, v20
	v_mov_b32_e32 v9, v20
	v_mov_b32_e32 v10, v20
	v_mov_b32_e32 v11, v20
	v_mov_b32_e32 v0, v20
	v_mov_b32_e32 v1, v20
	v_mov_b32_e32 v2, v20
	v_mov_b32_e32 v3, v20
	v_mov_b32_e32 v4, v20
	v_mov_b32_e32 v5, v20
	v_mov_b32_e32 v6, v20
	v_mov_b32_e32 v7, v20
.LBB0_835:
	v_lshl_add_u64 v[44:45], v[112:113], 0, s[6:7]
	s_mov_b32 s1, 0x17500000
	v_add_co_u32_e32 v142, vcc, s1, v44
	s_mov_b32 s9, 0x17510000
	s_nop 0
	v_addc_co_u32_e32 v143, vcc, 0, v45, vcc
	v_add_co_u32_e32 v150, vcc, s9, v44
	s_mov_b32 s19, 0x17520000
	s_nop 0
	v_addc_co_u32_e32 v151, vcc, 0, v45, vcc
	v_add_co_u32_e32 v164, vcc, s19, v44
	s_mov_b32 s20, 0x17530000
	s_nop 0
	v_addc_co_u32_e32 v165, vcc, 0, v45, vcc
	v_add_co_u32_e32 v128, vcc, s20, v44
	s_mov_b32 s21, 0x17540000
	s_nop 0
	v_addc_co_u32_e32 v129, vcc, 0, v45, vcc
	v_add_co_u32_e32 v126, vcc, s21, v44
	s_mov_b32 s22, 0x17550000
	s_nop 0
	v_addc_co_u32_e32 v127, vcc, 0, v45, vcc
	v_add_co_u32_e32 v124, vcc, s22, v44
	v_min_u32_e32 v46, 0x1fff, v136
	s_mov_b32 s23, 0x17560000
	v_addc_co_u32_e32 v125, vcc, 0, v45, vcc
	v_or_b32_e32 v46, s2, v46
	v_add_co_u32_e32 v122, vcc, s23, v44
	s_mov_b32 s24, 0x17570000
	s_nop 0
	v_addc_co_u32_e32 v123, vcc, 0, v45, vcc
	v_mad_u64_u32 v[200:201], s[20:21], v46, s79, v[116:117]
	v_add_co_u32_e32 v120, vcc, s24, v44
	v_mad_i32_i24 v201, s3, v180, v201
	global_load_dwordx4 v[32:35], v[118:119], off offset:-112
	global_load_dwordx4 v[36:39], v[118:119], off offset:-128
	global_load_dwordx4 v[40:43], v[118:119], off
	v_addc_co_u32_e32 v121, vcc, 0, v45, vcc
	global_load_dwordx4 v[56:59], v[128:129], off
	global_load_dwordx4 v[52:55], v[126:127], off
	global_load_dwordx4 v[48:51], v[124:125], off
	global_load_dwordx4 v[44:47], v[122:123], off
	global_load_dwordx4 v[138:141], v[142:143], off
	global_load_dwordx4 v[152:155], v[142:143], off offset:64
	global_load_dwordx4 v[156:159], v[150:151], off
	global_load_dwordx4 v[160:163], v[150:151], off offset:64
	global_load_dwordx4 v[188:191], v[164:165], off
	global_load_dwordx4 v[192:195], v[164:165], off offset:64
	global_load_dwordx4 v[196:199], v[200:201], off
	s_nop 0
	global_load_dwordx4 v[200:203], v[200:201], off offset:64
	s_add_u32 s6, s6, 0x80
	s_mov_b64 s[20:21], 0x100
	s_addc_u32 s7, s7, 0
	v_add_u32_e32 v136, 1, v136
	s_cmp_eq_u32 s6, s48
	s_waitcnt vmcnt(1)
	v_lshlrev_b32_e32 v142, 16, v196
	v_and_b32_e32 v143, 0xffff0000, v196
	v_lshlrev_b32_e32 v150, 16, v197
	v_and_b32_e32 v151, 0xffff0000, v197
	v_lshlrev_b32_e32 v164, 16, v198
	v_and_b32_e32 v165, 0xffff0000, v198
	v_lshlrev_b32_e32 v196, 16, v199
	v_and_b32_e32 v197, 0xffff0000, v199
	v_pk_add_f32 v[36:37], v[36:37], v[142:143]
	v_pk_add_f32 v[38:39], v[38:39], v[150:151]
	v_pk_add_f32 v[142:143], v[32:33], v[164:165]
	v_pk_add_f32 v[150:151], v[34:35], v[196:197]
	v_cvt_pk_bf16_f32 v32, v36, v37
	v_cvt_pk_bf16_f32 v33, v38, v39
	v_cvt_pk_bf16_f32 v34, v142, v143
	v_cvt_pk_bf16_f32 v35, v150, v151
	s_nop 1
	v_mfma_f32_16x16x32_bf16 v[28:31], v[138:141], v[32:35], v[28:31]
	global_load_dwordx4 v[36:39], v[128:129], off offset:64
	s_nop 0
	global_load_dwordx4 v[126:129], v[126:127], off offset:64
	s_nop 0
	global_load_dwordx4 v[138:141], v[124:125], off offset:64
	v_mfma_f32_16x16x32_bf16 v[16:19], v[156:159], v[32:35], v[16:19]
	global_load_dwordx4 v[122:125], v[122:123], off offset:64
	s_nop 0
	global_load_dwordx4 v[156:159], v[120:121], off
	global_load_dwordx4 v[196:199], v[120:121], off offset:64
	s_waitcnt vmcnt(6)
	v_lshlrev_b32_e32 v120, 16, v200
	v_and_b32_e32 v121, 0xffff0000, v200
	v_mfma_f32_16x16x32_bf16 v[24:27], v[188:191], v[32:35], v[24:27]
	global_load_dwordx4 v[188:191], v[118:119], off offset:16
	v_pk_add_f32 v[40:41], v[40:41], v[120:121]
	v_lshl_add_u64 v[118:119], v[118:119], 0, s[20:21]
	v_mfma_f32_16x16x32_bf16 v[20:23], v[56:59], v[32:35], v[20:23]
	v_lshlrev_b32_e32 v56, 16, v201
	v_and_b32_e32 v57, 0xffff0000, v201
	v_pk_add_f32 v[42:43], v[42:43], v[56:57]
	v_mfma_f32_16x16x32_bf16 v[12:15], v[52:55], v[32:35], v[12:15]
	v_lshlrev_b32_e32 v52, 16, v202
	v_and_b32_e32 v53, 0xffff0000, v202
	v_lshlrev_b32_e32 v54, 16, v203
	v_mfma_f32_16x16x32_bf16 v[8:11], v[48:51], v[32:35], v[8:11]
	v_and_b32_e32 v55, 0xffff0000, v203
	v_cvt_pk_bf16_f32 v40, v40, v41
	v_cvt_pk_bf16_f32 v41, v42, v43
	v_mfma_f32_16x16x32_bf16 v[0:3], v[44:47], v[32:35], v[0:3]
	s_waitcnt vmcnt(0)
	v_pk_add_f32 v[44:45], v[188:189], v[52:53]
	v_mfma_f32_16x16x32_bf16 v[4:7], v[156:159], v[32:35], v[4:7]
	v_add_f32_e64 v46, v190, v54
	v_add_f32_e64 v47, v191, v55
	v_cvt_pk_bf16_f32 v42, v44, v45
	v_cvt_pk_bf16_f32 v43, v46, v47
	s_nop 1
	v_mfma_f32_16x16x32_bf16 v[28:31], v[152:155], v[40:43], v[28:31]
	v_mfma_f32_16x16x32_bf16 v[16:19], v[160:163], v[40:43], v[16:19]
	v_mfma_f32_16x16x32_bf16 v[24:27], v[192:195], v[40:43], v[24:27]
	v_mfma_f32_16x16x32_bf16 v[20:23], v[36:39], v[40:43], v[20:23]
	v_mfma_f32_16x16x32_bf16 v[12:15], v[126:129], v[40:43], v[12:15]
	v_mfma_f32_16x16x32_bf16 v[8:11], v[138:141], v[40:43], v[8:11]
	v_mfma_f32_16x16x32_bf16 v[0:3], v[122:125], v[40:43], v[0:3]
	v_mfma_f32_16x16x32_bf16 v[4:7], v[196:199], v[40:43], v[4:7]
	s_cbranch_scc0 .LBB0_835
	s_nop 7
	v_mbcnt_lo_u32_b32 v236, -1, 0
	v_mbcnt_hi_u32_b32 v236, -1, v236
	s_lshl_b32 s49, s77, 13
	v_lshl_add_u32 v236, v236, 4, s49
	s_cmp_eq_u32 s47, 0
	s_cbranch_scc1 .Lcmpr_join
	ds_write_b128 v236, v[28:31]
	ds_write_b128 v236, v[16:19] offset:1024
	ds_write_b128 v236, v[24:27] offset:2048
	ds_write_b128 v236, v[20:23] offset:3072
	ds_write_b128 v236, v[12:15] offset:4096
	ds_write_b128 v236, v[8:11] offset:5120
	ds_write_b128 v236, v[0:3] offset:6144
	ds_write_b128 v236, v[4:7] offset:7168
	s_waitcnt lgkmcnt(0)
; __device__ __forceinline__ unsigned pk2(float lo, float hi) { return pg8::cvt_pk_bf16(lo, hi); }
; __device__ __forceinline__ float bflo(unsigned w) { return __uint_as_float(w << 16); }
; __device__ __forceinline__ float bfhi(unsigned w) { return __uint_as_float(w & 0xffff0000u); }
; __device__ __forceinline__ void compress_task(CArgs* Ap, int l, int task, int lane) {
;     ...
; #pragma unroll 2
;     for (int ks = 0; ks < 64; ++ks) {
;         const int itok = ks >> 1, d0 = 32 * (ks & 1) + 8 * g4;
;         int tok = 16 * n + itok; tok = tok > SEQ - 1 ? SEQ - 1 : tok;
;         const u32x4 raw = *(const u32x4*)(P + ((size_t)b * SEQ + tok) * NINP + colb + d0);
;         const f32x4 p0 = *(const f32x4*)(pos + itok * 64 + d0), p1 = *(const f32x4*)(pos + itok * 64 + d0 + 4);
;         u32x4 w;
;         w.x = pk2(bflo(raw.x) + p0[0], bfhi(raw.x) + p0[1]); w.y = pk2(bflo(raw.y) + p0[2], bfhi(raw.y) + p0[3]);
;         w.z = pk2(bflo(raw.z) + p1[0], bfhi(raw.z) + p1[1]); w.w = pk2(bflo(raw.w) + p1[2], bfhi(raw.w) + p1[3]);
;         const bf16x8 fb = __builtin_bit_cast(bf16x8, w);
; #pragma unroll
;         for (int h = 0; h < 8; ++h) { const bf16x8 wa = *(const bf16x8*)(W1t + (size_t)(16 * h + n16) * 2048 + 32 * ks + 8 * g4); acc[h] = __builtin_amdgcn_mfma_f32_16x16x32_bf16(wa, fb, acc[h], 0, 0, 0); }
;     }
.Lcmpr_join:
	s_barrier
	s_cmp_eq_u32 s47, 0
	s_cbranch_scc0 .LBB0_852
	v_add_u32_e32 v237, 0x2000, v236
	ds_read_b128 v[228:231], v237
	ds_read_b128 v[232:235], v237 offset:1024
	s_waitcnt lgkmcnt(1)
	v_add_f32_e32 v28, v28, v228
	v_add_f32_e32 v29, v29, v229
	v_add_f32_e32 v30, v30, v230
	v_add_f32_e32 v31, v31, v231
	s_waitcnt lgkmcnt(0)
	v_add_f32_e32 v16, v16, v232
	v_add_f32_e32 v17, v17, v233
	v_add_f32_e32 v18, v18, v234
	v_add_f32_e32 v19, v19, v235
	ds_read_b128 v[228:231], v237 offset:2048
	ds_read_b128 v[232:235], v237 offset:3072
	s_waitcnt lgkmcnt(1)
	v_add_f32_e32 v24, v24, v228
	v_add_f32_e32 v25, v25, v229
	v_add_f32_e32 v26, v26, v230
	v_add_f32_e32 v27, v27, v231
	s_waitcnt lgkmcnt(0)
	v_add_f32_e32 v20, v20, v232
	v_add_f32_e32 v21, v21, v233
	v_add_f32_e32 v22, v22, v234
	v_add_f32_e32 v23, v23, v235
	ds_read_b128 v[228:231], v237 offset:4096
	ds_read_b128 v[232:235], v237 offset:5120
	s_waitcnt lgkmcnt(1)
	v_add_f32_e32 v12, v12, v228
	v_add_f32_e32 v13, v13, v229
	v_add_f32_e32 v14, v14, v230
	v_add_f32_e32 v15, v15, v231
	s_waitcnt lgkmcnt(0)
	v_add_f32_e32 v8, v8, v232
	v_add_f32_e32 v9, v9, v233
	v_add_f32_e32 v10, v10, v234
	v_add_f32_e32 v11, v11, v235
	ds_read_b128 v[228:231], v237 offset:6144
	ds_read_b128 v[232:235], v237 offset:7168
	s_waitcnt lgkmcnt(1)
	v_add_f32_e32 v0, v0, v228
	v_add_f32_e32 v1, v1, v229
	v_add_f32_e32 v2, v2, v230
	v_add_f32_e32 v3, v3, v231
	s_waitcnt lgkmcnt(0)
	v_add_f32_e32 v4, v4, v232
	v_add_f32_e32 v5, v5, v233
	v_add_f32_e32 v6, v6, v234
	v_add_f32_e32 v7, v7, v235
	v_add_u32_e32 v237, 0x4000, v236
	ds_read_b128 v[228:231], v237
	ds_read_b128 v[232:235], v237 offset:1024
	s_waitcnt lgkmcnt(1)
	v_add_f32_e32 v28, v28, v228
	v_add_f32_e32 v29, v29, v229
	v_add_f32_e32 v30, v30, v230
	v_add_f32_e32 v31, v31, v231
	s_waitcnt lgkmcnt(0)
	v_add_f32_e32 v16, v16, v232
	v_add_f32_e32 v17, v17, v233
	v_add_f32_e32 v18, v18, v234
	v_add_f32_e32 v19, v19, v235
	ds_read_b128 v[228:231], v237 offset:2048
	ds_read_b128 v[232:235], v237 offset:3072
	s_waitcnt lgkmcnt(1)
	v_add_f32_e32 v24, v24, v228
	v_add_f32_e32 v25, v25, v229
	v_add_f32_e32 v26, v26, v230
	v_add_f32_e32 v27, v27, v231
	s_waitcnt lgkmcnt(0)
	v_add_f32_e32 v20, v20, v232
	v_add_f32_e32 v21, v21, v233
	v_add_f32_e32 v22, v22, v234
	v_add_f32_e32 v23, v23, v235
	ds_read_b128 v[228:231], v237 offset:4096
	ds_read_b128 v[232:235], v237 offset:5120
	s_waitcnt lgkmcnt(1)
	v_add_f32_e32 v12, v12, v228
	v_add_f32_e32 v13, v13, v229
	v_add_f32_e32 v14, v14, v230
	v_add_f32_e32 v15, v15, v231
	s_waitcnt lgkmcnt(0)
	v_add_f32_e32 v8, v8, v232
	v_add_f32_e32 v9, v9, v233
	v_add_f32_e32 v10, v10, v234
	v_add_f32_e32 v11, v11, v235
	ds_read_b128 v[228:231], v237 offset:6144
	ds_read_b128 v[232:235], v237 offset:7168
	s_waitcnt lgkmcnt(1)
	v_add_f32_e32 v0, v0, v228
	v_add_f32_e32 v1, v1, v229
	v_add_f32_e32 v2, v2, v230
	v_add_f32_e32 v3, v3, v231
	s_waitcnt lgkmcnt(0)
	v_add_f32_e32 v4, v4, v232
	v_add_f32_e32 v5, v5, v233
	v_add_f32_e32 v6, v6, v234
	v_add_f32_e32 v7, v7, v235
	v_add_u32_e32 v237, 0x6000, v236
	ds_read_b128 v[228:231], v237
	ds_read_b128 v[232:235], v237 offset:1024
	s_waitcnt lgkmcnt(1)
	v_add_f32_e32 v28, v28, v228
	v_add_f32_e32 v29, v29, v229
	v_add_f32_e32 v30, v30, v230
	v_add_f32_e32 v31, v31, v231
	s_waitcnt lgkmcnt(0)
	v_add_f32_e32 v16, v16, v232
	v_add_f32_e32 v17, v17, v233
	v_add_f32_e32 v18, v18, v234
	v_add_f32_e32 v19, v19, v235
	ds_read_b128 v[228:231], v237 offset:2048
	ds_read_b128 v[232:235], v237 offset:3072
	s_waitcnt lgkmcnt(1)
	v_add_f32_e32 v24, v24, v228
	v_add_f32_e32 v25, v25, v229
	v_add_f32_e32 v26, v26, v230
	v_add_f32_e32 v27, v27, v231
	s_waitcnt lgkmcnt(0)
	v_add_f32_e32 v20, v20, v232
	v_add_f32_e32 v21, v21, v233
	v_add_f32_e32 v22, v22, v234
	v_add_f32_e32 v23, v23, v235
	ds_read_b128 v[228:231], v237 offset:4096
	ds_read_b128 v[232:235], v237 offset:5120
	s_waitcnt lgkmcnt(1)
	v_add_f32_e32 v12, v12, v228
	v_add_f32_e32 v13, v13, v229
	v_add_f32_e32 v14, v14, v230
	v_add_f32_e32 v15, v15, v231
	s_waitcnt lgkmcnt(0)
	v_add_f32_e32 v8, v8, v232
	v_add_f32_e32 v9, v9, v233
	v_add_f32_e32 v10, v10, v234
	v_add_f32_e32 v11, v11, v235
	ds_read_b128 v[228:231], v237 offset:6144
	ds_read_b128 v[232:235], v237 offset:7168
	s_waitcnt lgkmcnt(1)
	v_add_f32_e32 v0, v0, v228
	v_add_f32_e32 v1, v1, v229
	v_add_f32_e32 v2, v2, v230
	v_add_f32_e32 v3, v3, v231
	s_waitcnt lgkmcnt(0)
; __device__ __forceinline__ unsigned pk2(float lo, float hi) { return pg8::cvt_pk_bf16(lo, hi); }
; __device__ __forceinline__ float gelu_tanh(float x) { const float z = 0.7978845608f * (x + 0.044715f * x * x * x); const float e = fexp(2.f * z); const float th = 1.f - 2.f * __builtin_amdgcn_rcpf(e + 1.f); return 0.5f * x * (1.f + th); }
; __device__ __forceinline__ void compress_task(CArgs* Ap, int l, int task, int lane) {
;     ...
; #pragma unroll
;     for (int pp = 0; pp < 4; ++pp) { float v[8];
; #pragma unroll
;         for (int i = 0; i < 4; ++i) { v[i] = gelu_tanh(acc[2 * pp][i]); v[4 + i] = gelu_tanh(acc[2 * pp + 1][i]); }
;         u32x4 w; w.x = pk2(v[0], v[1]); w.y = pk2(v[2], v[3]); w.z = pk2(v[4], v[5]); w.w = pk2(v[6], v[7]); hB[pp] = __builtin_bit_cast(bf16x8, w); }
	v_add_f32_e32 v4, v4, v232
	v_add_f32_e32 v5, v5, v233
	v_add_f32_e32 v6, v6, v234
	v_add_f32_e32 v7, v7, v235
	v_mul_f32_e32 v34, 0x3d372713, v29
	v_mul_f32_e32 v34, v29, v34
	v_fma_f32 v34, v29, v34, v29
	v_mul_f32_e32 v34, 0x3f4c422a, v34
	v_mul_f32_e32 v33, 0x3d372713, v16
	v_add_f32_e32 v34, v34, v34
	v_mul_f32_e32 v33, v16, v33
	v_mul_f32_e32 v34, 0x3fb8aa3b, v34
	v_fma_f32 v33, v16, v33, v16
	v_exp_f32_e32 v34, v34
	v_mul_f32_e32 v33, 0x3f4c422a, v33
	v_mul_f32_e32 v32, 0x3d372713, v28
	v_add_f32_e32 v33, v33, v33
	v_mul_f32_e32 v32, v28, v32
	v_mul_f32_e32 v33, 0x3fb8aa3b, v33
	v_fma_f32 v32, v28, v32, v28
	v_exp_f32_e32 v35, v33
	v_add_f32_e32 v33, 1.0, v34
	v_mul_f32_e32 v34, 0x3d372713, v17
	v_mul_f32_e32 v32, 0x3f4c422a, v32
	v_mul_f32_e32 v34, v17, v34
	v_add_f32_e32 v32, v32, v32
	v_fma_f32 v34, v17, v34, v17
	v_mul_f32_e32 v32, 0x3fb8aa3b, v32
	v_mul_f32_e32 v34, 0x3f4c422a, v34
	v_exp_f32_e32 v32, v32
	v_add_f32_e32 v34, v34, v34
	v_mul_f32_e32 v34, 0x3fb8aa3b, v34
	v_exp_f32_e32 v36, v34
	v_add_f32_e32 v32, 1.0, v32
	v_rcp_f32_e32 v32, v32
	v_rcp_f32_e32 v33, v33
	v_add_f32_e32 v34, 1.0, v35
	v_add_f32_e32 v35, 1.0, v36
	v_rcp_f32_e32 v34, v34
	v_rcp_f32_e32 v35, v35
	v_pk_fma_f32 v[32:33], v[32:33], 2.0, 1.0 op_sel_hi:[1,0,0] neg_lo:[1,0,0] neg_hi:[1,0,0]
	v_pk_mul_f32 v[28:29], v[28:29], 0.5 op_sel_hi:[1,0]
	v_pk_add_f32 v[32:33], v[32:33], 1.0 op_sel_hi:[1,0]
	v_pk_mul_f32 v[16:17], v[16:17], 0.5 op_sel_hi:[1,0]
	v_pk_mul_f32 v[28:29], v[28:29], v[32:33]
	v_pk_fma_f32 v[32:33], v[34:35], 2.0, 1.0 op_sel_hi:[1,0,0] neg_lo:[1,0,0] neg_hi:[1,0,0]
	v_mul_f32_e32 v34, 0x3d372713, v30
	v_mul_f32_e32 v34, v30, v34
	v_fma_f32 v34, v30, v34, v30
	v_mul_f32_e32 v34, 0x3f4c422a, v34
	v_add_f32_e32 v34, v34, v34
	v_mul_f32_e32 v34, 0x3fb8aa3b, v34
	v_exp_f32_e32 v34, v34
	v_pk_add_f32 v[32:33], v[32:33], 1.0 op_sel_hi:[1,0]
	s_lshl_b32 s0, s0, 5
	v_pk_mul_f32 v[32:33], v[16:17], v[32:33]
	v_add_f32_e32 v16, 1.0, v34
	v_mul_f32_e32 v34, 0x3d372713, v31
	v_mul_f32_e32 v34, v31, v34
	v_fma_f32 v34, v31, v34, v31
	v_mul_f32_e32 v34, 0x3f4c422a, v34
	v_mul_f32_e32 v17, 0x3d372713, v18
	v_add_f32_e32 v34, v34, v34
	v_mul_f32_e32 v17, v18, v17
	v_mul_f32_e32 v34, 0x3fb8aa3b, v34
	v_fma_f32 v17, v18, v17, v18
	v_exp_f32_e32 v34, v34
	v_mul_f32_e32 v17, 0x3f4c422a, v17
	v_add_f32_e32 v17, v17, v17
	v_mul_f32_e32 v17, 0x3fb8aa3b, v17
	v_exp_f32_e32 v35, v17
	v_add_f32_e32 v17, 1.0, v34
	v_mul_f32_e32 v34, 0x3d372713, v19
	v_mul_f32_e32 v34, v19, v34
	v_fma_f32 v34, v19, v34, v19
	v_mul_f32_e32 v34, 0x3f4c422a, v34
	v_add_f32_e32 v34, v34, v34
	v_mul_f32_e32 v34, 0x3fb8aa3b, v34
	v_exp_f32_e32 v36, v34
	v_rcp_f32_e32 v16, v16
	v_rcp_f32_e32 v17, v17
	v_add_f32_e32 v34, 1.0, v35
	v_add_f32_e32 v35, 1.0, v36
	v_rcp_f32_e32 v34, v34
	v_rcp_f32_e32 v35, v35
	v_pk_fma_f32 v[16:17], v[16:17], 2.0, 1.0 op_sel_hi:[1,0,0] neg_lo:[1,0,0] neg_hi:[1,0,0]
	v_pk_mul_f32 v[30:31], v[30:31], 0.5 op_sel_hi:[1,0]
	v_pk_add_f32 v[16:17], v[16:17], 1.0 op_sel_hi:[1,0]
	v_pk_mul_f32 v[18:19], v[18:19], 0.5 op_sel_hi:[1,0]
	v_pk_mul_f32 v[30:31], v[30:31], v[16:17]
	v_pk_fma_f32 v[16:17], v[34:35], 2.0, 1.0 op_sel_hi:[1,0,0] neg_lo:[1,0,0] neg_hi:[1,0,0]
	s_lshl_b32 s1, s8, 3
	v_pk_add_f32 v[16:17], v[16:17], 1.0 op_sel_hi:[1,0]
	s_or_b32 s0, s1, s0
	v_pk_mul_f32 v[34:35], v[18:19], v[16:17]
	v_mul_f32_e32 v17, 0x3d372713, v24
	v_mul_f32_e32 v17, v24, v17
	v_fma_f32 v17, v24, v17, v24
	v_mul_f32_e32 v17, 0x3f4c422a, v17
	v_add_f32_e32 v17, v17, v17
	v_mul_f32_e32 v17, 0x3fb8aa3b, v17
	v_cvt_pk_bf16_f32 v16, v28, v29
	v_exp_f32_e32 v28, v17
	v_cvt_pk_bf16_f32 v17, v30, v31
	v_mul_f32_e32 v30, 0x3d372713, v25
	v_mul_f32_e32 v30, v25, v30
	v_fma_f32 v30, v25, v30, v25
	v_mul_f32_e32 v30, 0x3f4c422a, v30
	v_mul_f32_e32 v29, 0x3d372713, v20
	v_add_f32_e32 v30, v30, v30
	v_mul_f32_e32 v29, v20, v29
	v_mul_f32_e32 v30, 0x3fb8aa3b, v30
	v_fma_f32 v29, v20, v29, v20
	v_exp_f32_e32 v30, v30
	v_mul_f32_e32 v29, 0x3f4c422a, v29
	v_add_f32_e32 v29, v29, v29
	v_mul_f32_e32 v29, 0x3fb8aa3b, v29
	v_exp_f32_e32 v31, v29
	v_add_f32_e32 v29, 1.0, v30
	v_mul_f32_e32 v30, 0x3d372713, v21
	v_mul_f32_e32 v30, v21, v30
	v_fma_f32 v30, v21, v30, v21
	v_mul_f32_e32 v30, 0x3f4c422a, v30
	v_add_f32_e32 v30, v30, v30
	v_mul_f32_e32 v30, 0x3fb8aa3b, v30
	v_cvt_pk_bf16_f32 v18, v32, v33
	v_exp_f32_e32 v32, v30
	v_add_f32_e32 v28, 1.0, v28
	v_rcp_f32_e32 v28, v28
	v_rcp_f32_e32 v29, v29
	v_add_f32_e32 v30, 1.0, v31
	v_add_f32_e32 v31, 1.0, v32
	v_rcp_f32_e32 v30, v30
	v_rcp_f32_e32 v31, v31
	v_pk_fma_f32 v[28:29], v[28:29], 2.0, 1.0 op_sel_hi:[1,0,0] neg_lo:[1,0,0] neg_hi:[1,0,0]
	v_pk_mul_f32 v[24:25], v[24:25], 0.5 op_sel_hi:[1,0]
	v_pk_add_f32 v[28:29], v[28:29], 1.0 op_sel_hi:[1,0]
	v_pk_mul_f32 v[20:21], v[20:21], 0.5 op_sel_hi:[1,0]
	v_pk_mul_f32 v[24:25], v[24:25], v[28:29]
	v_pk_fma_f32 v[28:29], v[30:31], 2.0, 1.0 op_sel_hi:[1,0,0] neg_lo:[1,0,0] neg_hi:[1,0,0]
	v_mul_f32_e32 v30, 0x3d372713, v26
	v_mul_f32_e32 v30, v26, v30
	v_fma_f32 v30, v26, v30, v26
	v_mul_f32_e32 v30, 0x3f4c422a, v30
	v_add_f32_e32 v30, v30, v30
	v_mul_f32_e32 v30, 0x3fb8aa3b, v30
	v_exp_f32_e32 v30, v30
	v_pk_add_f32 v[28:29], v[28:29], 1.0 op_sel_hi:[1,0]
	v_cvt_pk_bf16_f32 v19, v34, v35
	v_pk_mul_f32 v[28:29], v[20:21], v[28:29]
	v_add_f32_e32 v20, 1.0, v30
	v_mul_f32_e32 v30, 0x3d372713, v27
	v_mul_f32_e32 v30, v27, v30
	v_fma_f32 v30, v27, v30, v27
	v_mul_f32_e32 v30, 0x3f4c422a, v30
	v_mul_f32_e32 v21, 0x3d372713, v22
	v_add_f32_e32 v30, v30, v30
	v_mul_f32_e32 v21, v22, v21
	v_mul_f32_e32 v30, 0x3fb8aa3b, v30
	v_fma_f32 v21, v22, v21, v22
	v_exp_f32_e32 v30, v30
	v_mul_f32_e32 v21, 0x3f4c422a, v21
; __device__ __forceinline__ unsigned pk2(float lo, float hi) { return pg8::cvt_pk_bf16(lo, hi); }
; __device__ __forceinline__ float gelu_tanh(float x) { const float z = 0.7978845608f * (x + 0.044715f * x * x * x); const float e = fexp(2.f * z); const float th = 1.f - 2.f * __builtin_amdgcn_rcpf(e + 1.f); return 0.5f * x * (1.f + th); }
; __device__ __forceinline__ void compress_task(CArgs* Ap, int l, int task, int lane) {
;     ...
; #pragma unroll
;     for (int pp = 0; pp < 4; ++pp) { float v[8];
; #pragma unroll
;         for (int i = 0; i < 4; ++i) { v[i] = gelu_tanh(acc[2 * pp][i]); v[4 + i] = gelu_tanh(acc[2 * pp + 1][i]); }
;         u32x4 w; w.x = pk2(v[0], v[1]); w.y = pk2(v[2], v[3]); w.z = pk2(v[4], v[5]); w.w = pk2(v[6], v[7]); hB[pp] = __builtin_bit_cast(bf16x8, w); }
	v_add_f32_e32 v21, v21, v21
	v_mul_f32_e32 v21, 0x3fb8aa3b, v21
	v_exp_f32_e32 v31, v21
	v_add_f32_e32 v21, 1.0, v30
	v_mul_f32_e32 v30, 0x3d372713, v23
	v_mul_f32_e32 v30, v23, v30
	v_fma_f32 v30, v23, v30, v23
	v_mul_f32_e32 v30, 0x3f4c422a, v30
	v_add_f32_e32 v30, v30, v30
	v_mul_f32_e32 v30, 0x3fb8aa3b, v30
	v_exp_f32_e32 v32, v30
	v_rcp_f32_e32 v20, v20
	v_rcp_f32_e32 v21, v21
	v_add_f32_e32 v30, 1.0, v31
	v_add_f32_e32 v31, 1.0, v32
	v_rcp_f32_e32 v30, v30
	v_rcp_f32_e32 v31, v31
	v_pk_fma_f32 v[20:21], v[20:21], 2.0, 1.0 op_sel_hi:[1,0,0] neg_lo:[1,0,0] neg_hi:[1,0,0]
	v_pk_mul_f32 v[26:27], v[26:27], 0.5 op_sel_hi:[1,0]
	v_pk_add_f32 v[20:21], v[20:21], 1.0 op_sel_hi:[1,0]
	v_pk_mul_f32 v[22:23], v[22:23], 0.5 op_sel_hi:[1,0]
	v_pk_mul_f32 v[26:27], v[26:27], v[20:21]
	v_pk_fma_f32 v[20:21], v[30:31], 2.0, 1.0 op_sel_hi:[1,0,0] neg_lo:[1,0,0] neg_hi:[1,0,0]
	s_bfe_u32 s1, s10, 0x30003
	v_pk_add_f32 v[20:21], v[20:21], 1.0 op_sel_hi:[1,0]
	s_or_b32 s0, s0, s1
	v_pk_mul_f32 v[30:31], v[22:23], v[20:21]
	v_mul_f32_e32 v21, 0x3d372713, v12
	v_mul_f32_e32 v21, v12, v21
	v_fma_f32 v21, v12, v21, v12
	v_mul_f32_e32 v21, 0x3f4c422a, v21
	v_add_f32_e32 v21, v21, v21
	v_mul_f32_e32 v21, 0x3fb8aa3b, v21
	v_cvt_pk_bf16_f32 v20, v24, v25
	v_exp_f32_e32 v24, v21
	v_cvt_pk_bf16_f32 v21, v26, v27
	v_mul_f32_e32 v26, 0x3d372713, v13
	v_mul_f32_e32 v26, v13, v26
	v_fma_f32 v26, v13, v26, v13
	v_mul_f32_e32 v26, 0x3f4c422a, v26
	v_mul_f32_e32 v25, 0x3d372713, v8
	v_add_f32_e32 v26, v26, v26
	v_mul_f32_e32 v25, v8, v25
	v_mul_f32_e32 v26, 0x3fb8aa3b, v26
	v_fma_f32 v25, v8, v25, v8
	v_exp_f32_e32 v26, v26
	v_mul_f32_e32 v25, 0x3f4c422a, v25
	v_add_f32_e32 v25, v25, v25
	v_mul_f32_e32 v25, 0x3fb8aa3b, v25
	v_exp_f32_e32 v27, v25
	v_add_f32_e32 v25, 1.0, v26
	v_mul_f32_e32 v26, 0x3d372713, v9
	v_mul_f32_e32 v26, v9, v26
	v_fma_f32 v26, v9, v26, v9
	v_mul_f32_e32 v26, 0x3f4c422a, v26
	v_add_f32_e32 v26, v26, v26
	v_mul_f32_e32 v26, 0x3fb8aa3b, v26
	v_cvt_pk_bf16_f32 v22, v28, v29
	v_exp_f32_e32 v28, v26
	v_add_f32_e32 v24, 1.0, v24
	v_rcp_f32_e32 v24, v24
	v_rcp_f32_e32 v25, v25
	v_add_f32_e32 v26, 1.0, v27
	v_add_f32_e32 v27, 1.0, v28
	v_rcp_f32_e32 v26, v26
	v_rcp_f32_e32 v27, v27
	v_pk_fma_f32 v[24:25], v[24:25], 2.0, 1.0 op_sel_hi:[1,0,0] neg_lo:[1,0,0] neg_hi:[1,0,0]
	v_pk_mul_f32 v[12:13], v[12:13], 0.5 op_sel_hi:[1,0]
	v_pk_add_f32 v[24:25], v[24:25], 1.0 op_sel_hi:[1,0]
	v_pk_mul_f32 v[8:9], v[8:9], 0.5 op_sel_hi:[1,0]
	v_pk_mul_f32 v[12:13], v[12:13], v[24:25]
	v_pk_fma_f32 v[24:25], v[26:27], 2.0, 1.0 op_sel_hi:[1,0,0] neg_lo:[1,0,0] neg_hi:[1,0,0]
	v_mul_f32_e32 v26, 0x3d372713, v14
	v_mul_f32_e32 v26, v14, v26
	v_fma_f32 v26, v14, v26, v14
	v_mul_f32_e32 v26, 0x3f4c422a, v26
	v_add_f32_e32 v26, v26, v26
	v_mul_f32_e32 v26, 0x3fb8aa3b, v26
	v_exp_f32_e32 v26, v26
	v_pk_add_f32 v[24:25], v[24:25], 1.0 op_sel_hi:[1,0]
	v_cvt_pk_bf16_f32 v23, v30, v31
	v_pk_mul_f32 v[24:25], v[8:9], v[24:25]
	v_add_f32_e32 v8, 1.0, v26
	v_mul_f32_e32 v26, 0x3d372713, v15
	v_mul_f32_e32 v26, v15, v26
	v_fma_f32 v26, v15, v26, v15
	v_mul_f32_e32 v26, 0x3f4c422a, v26
	v_mul_f32_e32 v9, 0x3d372713, v10
	v_add_f32_e32 v26, v26, v26
	v_mul_f32_e32 v9, v10, v9
	v_mul_f32_e32 v26, 0x3fb8aa3b, v26
	v_fma_f32 v9, v10, v9, v10
	v_exp_f32_e32 v26, v26
	v_mul_f32_e32 v9, 0x3f4c422a, v9
	v_add_f32_e32 v9, v9, v9
	v_mul_f32_e32 v9, 0x3fb8aa3b, v9
	v_exp_f32_e32 v27, v9
	v_add_f32_e32 v9, 1.0, v26
	v_mul_f32_e32 v26, 0x3d372713, v11
	v_mul_f32_e32 v26, v11, v26
	v_fma_f32 v26, v11, v26, v11
	v_mul_f32_e32 v26, 0x3f4c422a, v26
	v_add_f32_e32 v26, v26, v26
	v_mul_f32_e32 v26, 0x3fb8aa3b, v26
	v_exp_f32_e32 v28, v26
	v_rcp_f32_e32 v8, v8
	v_rcp_f32_e32 v9, v9
	v_add_f32_e32 v26, 1.0, v27
	v_add_f32_e32 v27, 1.0, v28
	v_rcp_f32_e32 v26, v26
	v_rcp_f32_e32 v27, v27
	v_pk_fma_f32 v[8:9], v[8:9], 2.0, 1.0 op_sel_hi:[1,0,0] neg_lo:[1,0,0] neg_hi:[1,0,0]
	v_pk_mul_f32 v[14:15], v[14:15], 0.5 op_sel_hi:[1,0]
	v_pk_add_f32 v[8:9], v[8:9], 1.0 op_sel_hi:[1,0]
	v_pk_mul_f32 v[10:11], v[10:11], 0.5 op_sel_hi:[1,0]
	v_pk_mul_f32 v[14:15], v[14:15], v[8:9]
	v_pk_fma_f32 v[8:9], v[26:27], 2.0, 1.0 op_sel_hi:[1,0,0] neg_lo:[1,0,0] neg_hi:[1,0,0]
	s_ashr_i32 s1, s0, 31
	v_pk_add_f32 v[8:9], v[8:9], 1.0 op_sel_hi:[1,0]
	s_lshl_b32 s2, s10, 4
	v_pk_mul_f32 v[26:27], v[10:11], v[8:9]
	v_mul_f32_e32 v9, 0x3d372713, v0
	v_mul_f32_e32 v9, v0, v9
	v_fma_f32 v9, v0, v9, v0
	v_mul_f32_e32 v9, 0x3f4c422a, v9
	v_add_f32_e32 v9, v9, v9
	v_mul_f32_e32 v9, 0x3fb8aa3b, v9
	v_cvt_pk_bf16_f32 v8, v12, v13
	v_exp_f32_e32 v12, v9
; __device__ __forceinline__ unsigned pk2(float lo, float hi) { return pg8::cvt_pk_bf16(lo, hi); }
; __device__ __forceinline__ bf16_t f2bf(float f) { return (bf16_t)(pk2(f, f) & 0xffffu); }
; __device__ __forceinline__ int kswz(int key, int d) { return ((((key >> 4) * 2 + (d >> 5)) * 64) + ((d >> 3) & 3) * 16 + (key & 15)) * 8 + (d & 7); }
; __device__ __forceinline__ int vswz(int d, int key) { const int k = key & 31; return ((((d >> 4) * 2 + (key >> 5)) * 64) + ((k & 15) >> 2) * 16 + (d & 15)) * 8 + (k & 3) + 4 * (k >> 4); }
; __device__ __forceinline__ void compress_task(CArgs* Ap, int l, int task, int lane) {
;     ...
;     for (int dt = 0; dt < 4; ++dt) {
;         f32x4 o = (f32x4){0.f, 0.f, 0.f, 0.f};
; #pragma unroll
;         for (int pp = 0; pp < 4; ++pp) { const bf16_t* wrow = W2t + (size_t)(16 * dt + n16) * 128 + 32 * pp + 4 * g4;
;             const u32x2 lo = *(const u32x2*)wrow, hi = *(const u32x2*)(wrow + 16);
;             u32x4 w; w.x = lo.x; w.y = lo.y; w.z = hi.x; w.w = hi.y;
;             o = __builtin_amdgcn_mfma_f32_16x16x32_bf16(__builtin_bit_cast(bf16x8, w), hB[pp], o, 0, 0, 0); }
;         if (kv == 0) { u32x2 w; w.x = pk2(o[0], o[1]); w.y = pk2(o[2], o[3]); *(u32x2*)(KC + (size_t)((b * 4 + g) * 8 + (n >> 6)) * 4096 + kswz(n & 63, 16 * dt + 4 * g4)) = w; }
;         else {
; #pragma unroll
;             for (int i = 0; i < 4; ++i) VCT[(size_t)((b * 4 + g) * 8 + (n >> 6)) * 4096 + vswz(16 * dt + 4 * g4 + i, n & 63)] = f2bf(o[i]); }
	v_cvt_pk_bf16_f32 v11, v26, v27
	v_mul_f32_e32 v13, 0x3d372713, v1
	global_load_dwordx2 v[26:27], v[60:61], off
	global_load_dwordx2 v[28:29], v[60:61], off offset:32
	v_mul_f32_e32 v13, v1, v13
	v_fma_f32 v13, v1, v13, v1
	v_add_f32_e32 v12, 1.0, v12
	v_mul_f32_e32 v13, 0x3f4c422a, v13
	v_cvt_pk_bf16_f32 v10, v24, v25
	v_rcp_f32_e32 v24, v12
	v_mul_f32_e32 v12, 0x3d372713, v4
	v_add_f32_e32 v13, v13, v13
	global_load_dwordx2 v[30:31], v[60:61], off offset:64
	global_load_dwordx2 v[32:33], v[60:61], off offset:96
	v_mul_f32_e32 v12, v4, v12
	v_mul_f32_e32 v13, 0x3fb8aa3b, v13
	v_fma_f32 v12, v4, v12, v4
	v_exp_f32_e32 v13, v13
	v_mul_f32_e32 v12, 0x3f4c422a, v12
	v_add_f32_e32 v12, v12, v12
	global_load_dwordx2 v[34:35], v[60:61], off offset:128
	global_load_dwordx2 v[36:37], v[60:61], off offset:160
	v_mul_f32_e32 v12, 0x3fb8aa3b, v12
	v_exp_f32_e32 v38, v12
	v_add_f32_e32 v12, 1.0, v13
	v_rcp_f32_e32 v25, v12
	v_mul_f32_e32 v12, 0x3d372713, v5
	v_cvt_pk_bf16_f32 v9, v14, v15
	v_mul_f32_e32 v39, v5, v12
	global_load_dwordx2 v[12:13], v[60:61], off offset:192
	global_load_dwordx2 v[14:15], v[60:61], off offset:224
	v_fma_f32 v39, v5, v39, v5
	v_mul_f32_e32 v39, 0x3f4c422a, v39
	v_add_f32_e32 v39, v39, v39
	v_mul_f32_e32 v39, 0x3fb8aa3b, v39
	v_exp_f32_e32 v39, v39
	v_add_f32_e32 v38, 1.0, v38
	v_rcp_f32_e32 v38, v38
	v_pk_fma_f32 v[24:25], v[24:25], 2.0, 1.0 op_sel_hi:[1,0,0] neg_lo:[1,0,0] neg_hi:[1,0,0]
	v_add_f32_e32 v39, 1.0, v39
	v_rcp_f32_e32 v39, v39
	v_pk_mul_f32 v[0:1], v[0:1], 0.5 op_sel_hi:[1,0]
	v_pk_add_f32 v[24:25], v[24:25], 1.0 op_sel_hi:[1,0]
	v_pk_mul_f32 v[4:5], v[4:5], 0.5 op_sel_hi:[1,0]
	v_pk_mul_f32 v[0:1], v[0:1], v[24:25]
	v_pk_fma_f32 v[24:25], v[38:39], 2.0, 1.0 op_sel_hi:[1,0,0] neg_lo:[1,0,0] neg_hi:[1,0,0]
	v_mul_f32_e32 v38, 0x3d372713, v2
	v_mul_f32_e32 v38, v2, v38
	v_fma_f32 v38, v2, v38, v2
	v_mul_f32_e32 v38, 0x3f4c422a, v38
	v_add_f32_e32 v38, v38, v38
	v_mul_f32_e32 v38, 0x3fb8aa3b, v38
	v_exp_f32_e32 v38, v38
	v_pk_add_f32 v[24:25], v[24:25], 1.0 op_sel_hi:[1,0]
	v_cvt_pk_bf16_f32 v0, v0, v1
	v_pk_mul_f32 v[4:5], v[4:5], v[24:25]
	v_add_f32_e32 v24, 1.0, v38
	v_mul_f32_e32 v38, 0x3d372713, v3
	v_mul_f32_e32 v38, v3, v38
	v_fma_f32 v38, v3, v38, v3
	v_mul_f32_e32 v38, 0x3f4c422a, v38
	v_mul_f32_e32 v25, 0x3d372713, v6
	v_add_f32_e32 v38, v38, v38
	v_mul_f32_e32 v25, v6, v25
	v_mul_f32_e32 v38, 0x3fb8aa3b, v38
	v_fma_f32 v25, v6, v25, v6
	v_exp_f32_e32 v38, v38
	v_mul_f32_e32 v25, 0x3f4c422a, v25
	v_add_f32_e32 v25, v25, v25
	v_mul_f32_e32 v25, 0x3fb8aa3b, v25
	v_exp_f32_e32 v39, v25
	v_add_f32_e32 v25, 1.0, v38
	v_mul_f32_e32 v38, 0x3d372713, v7
	v_mul_f32_e32 v38, v7, v38
	v_fma_f32 v38, v7, v38, v7
	v_mul_f32_e32 v38, 0x3f4c422a, v38
	v_add_f32_e32 v38, v38, v38
	v_mul_f32_e32 v38, 0x3fb8aa3b, v38
	v_exp_f32_e32 v40, v38
	v_rcp_f32_e32 v24, v24
	v_rcp_f32_e32 v25, v25
	v_add_f32_e32 v38, 1.0, v39
	v_add_f32_e32 v39, 1.0, v40
	v_rcp_f32_e32 v38, v38
	v_rcp_f32_e32 v39, v39
	v_pk_fma_f32 v[24:25], v[24:25], 2.0, 1.0 op_sel_hi:[1,0,0] neg_lo:[1,0,0] neg_hi:[1,0,0]
	v_pk_mul_f32 v[2:3], v[2:3], 0.5 op_sel_hi:[1,0]
	v_pk_add_f32 v[24:25], v[24:25], 1.0 op_sel_hi:[1,0]
	v_pk_mul_f32 v[6:7], v[6:7], 0.5 op_sel_hi:[1,0]
	v_pk_mul_f32 v[2:3], v[2:3], v[24:25]
	v_pk_fma_f32 v[24:25], v[38:39], 2.0, 1.0 op_sel_hi:[1,0,0] neg_lo:[1,0,0] neg_hi:[1,0,0]
	v_cvt_pk_bf16_f32 v1, v2, v3
	v_pk_add_f32 v[24:25], v[24:25], 1.0 op_sel_hi:[1,0]
	v_cvt_pk_bf16_f32 v2, v4, v5
	v_pk_mul_f32 v[6:7], v[6:7], v[24:25]
	v_and_or_b32 v24, s2, 64, v133
	v_cvt_pk_bf16_f32 v3, v6, v7
	s_waitcnt vmcnt(6)
	v_mfma_f32_16x16x32_bf16 v[4:7], v[26:29], v[16:19], 0
	s_lshl_b32 s2, s10, 1
	s_lshl_b64 s[0:1], s[0:1], 13
	s_add_u32 s6, s13, s0
	s_waitcnt vmcnt(4)
	v_mfma_f32_16x16x32_bf16 v[4:7], v[30:33], v[20:23], v[4:7]
	v_and_or_b32 v25, s2, 4, v130
	s_addc_u32 s7, s14, s1
	s_add_u32 s0, s11, s0
	s_waitcnt vmcnt(2)
	v_mfma_f32_16x16x32_bf16 v[4:7], v[34:37], v[8:11], v[4:7]
	s_addc_u32 s1, s12, s1
	s_mov_b64 s[2:3], -1
	s_and_b64 vcc, exec, s[4:5]
	s_waitcnt vmcnt(0)
	v_mfma_f32_16x16x32_bf16 v[4:7], v[12:15], v[0:3], v[4:7]
	v_lshlrev_b32_e32 v12, 1, v25
	v_lshl_or_b32 v144, v24, 4, v12
	s_cbranch_vccz .LBB0_838
	s_nop 4
	v_cvt_pk_bf16_f32 v12, v4, s0
	global_store_short v144, v12, s[6:7]
	v_cvt_pk_bf16_f32 v12, v5, s0
	global_store_short v144, v12, s[6:7] offset:16
	v_cvt_pk_bf16_f32 v12, v6, s0
	global_store_short v144, v12, s[6:7] offset:32
	v_cvt_pk_bf16_f32 v12, v7, s0
	s_mov_b64 s[2:3], 0
	global_store_short v144, v12, s[6:7] offset:48
